# MLA: waves 4-7 start each tile iteration one s_sleep 2 later than their SIMD partners (stagger)
# baseline (speedup 1.0000x reference)
.Lmla_loop:
.Lmla_it0:
	s_cmp_lt_u32 s39, 4
	s_cbranch_scc1 .Lmla_nostag0
	s_sleep 2
.Lmla_nostag0:
	s_add_i32 s42, s65, 3
	s_min_u32 s42, s42, s44
	s_lshl_b64 s[6:7], s[42:43], 17
	v_lshl_add_u64 v[242:243], v[190:191], 0, s[6:7]
	s_lshl_b64 s[6:7], s[42:43], 12
	v_lshl_add_u64 v[244:245], v[194:195], 0, s[6:7]
	s_add_i32 s42, s65, 2
	s_min_u32 s42, s42, s44
	s_lshl_b64 s[6:7], s[42:43], 17
	v_lshl_add_u64 v[246:247], v[192:193], 0, s[6:7]
	global_load_dwordx4 v[6:9], v[242:243], off
	global_load_dwordx4 v[10:13], v[246:247], off
	global_load_dwordx4 v[2:5], v[244:245], off
	s_cmp_ge_u32 s65, s45
	s_cbranch_scc1 .Lmla_skip0
	s_add_i32 s41, s65, 1
	s_cmp_ge_u32 s41, s64
	s_cselect_b32 s7, 1, 0
	s_cmp_lt_u32 s41, s45
	s_cselect_b32 s26, 1, 0
	s_and_b32 s56, s7, s26
	s_lshl_b32 s27, s41, 6
	ds_read_b128 v[164:167], v210 offset:25600
	ds_read_b128 v[168:171], v210 offset:25632
	ds_read_b128 v[172:175], v210 offset:25664
	ds_read_b128 v[214:217], v210 offset:25696
	ds_read_b128 v[218:221], v210 offset:25728
	ds_read_b128 v[222:225], v210 offset:25760
	v_exp_f32_e32 v64, v64
	v_exp_f32_e32 v65, v65
	v_exp_f32_e32 v66, v66
	v_exp_f32_e32 v67, v67
	s_waitcnt lgkmcnt(5)
	v_mfma_f32_32x32x16_bf16 v[132:147], v[164:167], v[96:99], v[48:63]
	ds_read_b128 v[164:167], v210 offset:32256
	v_add_f32_e32 v14, v64, v65
	v_add_f32_e32 v15, v66, v67
	v_exp_f32_e32 v68, v68
	v_exp_f32_e32 v69, v69
	s_waitcnt lgkmcnt(5)
	v_mfma_f32_32x32x16_bf16 v[132:147], v[168:171], v[100:103], v[132:147]
	ds_read_b128 v[168:171], v210 offset:32288
	v_exp_f32_e32 v70, v70
	v_exp_f32_e32 v71, v71
	v_add_f32_e32 v14, v14, v15
	v_add_f32_e32 v15, v68, v69
	s_waitcnt lgkmcnt(5)
	v_mfma_f32_32x32x16_bf16 v[132:147], v[172:175], v[104:107], v[132:147]
	ds_read_b128 v[172:175], v210 offset:32320
	v_add_f32_e32 v213, v70, v71
	v_cvt_pk_bf16_f32 v64, v64, v65
	v_cvt_pk_bf16_f32 v65, v66, v67
	v_cvt_pk_bf16_f32 v66, v68, v69
	v_cvt_pk_bf16_f32 v67, v70, v71
	s_waitcnt lgkmcnt(5)
	v_mfma_f32_32x32x16_bf16 v[132:147], v[214:217], v[108:111], v[132:147]
	ds_read_b128 v[214:217], v210 offset:32352
	v_exp_f32_e32 v72, v72
	v_exp_f32_e32 v73, v73
	v_exp_f32_e32 v74, v74
	v_exp_f32_e32 v75, v75
	s_waitcnt lgkmcnt(5)
	v_mfma_f32_32x32x16_bf16 v[132:147], v[218:221], v[112:115], v[132:147]
	ds_read_b128 v[218:221], v210 offset:32384
	v_add_f32_e32 v14, v14, v15
	v_add_f32_e32 v14, v14, v213
	v_exp_f32_e32 v76, v76
	v_exp_f32_e32 v77, v77
	s_waitcnt lgkmcnt(5)
	v_mfma_f32_32x32x16_bf16 v[132:147], v[222:225], v[116:119], v[132:147]
	ds_read_b128 v[222:225], v210 offset:32416
	v_exp_f32_e32 v78, v78
	v_exp_f32_e32 v79, v79
	v_add_f32_e32 v15, v72, v73
	v_add_f32_e32 v213, v74, v75
	s_waitcnt lgkmcnt(5)
	v_mfma_f32_32x32x16_bf16 v[148:163], v[164:167], v[96:99], v[48:63]
	ds_read_b64_tr_b16 v[226:227], v211 offset:13312
	ds_read_b64_tr_b16 v[228:229], v211 offset:14848
	v_add_f32_e32 v248, v76, v77
	v_add_f32_e32 v249, v78, v79
	v_cvt_pk_bf16_f32 v68, v72, v73
	v_cvt_pk_bf16_f32 v69, v74, v75
	v_cvt_pk_bf16_f32 v70, v76, v77
	v_cvt_pk_bf16_f32 v71, v78, v79
	s_waitcnt lgkmcnt(6)
	v_mfma_f32_32x32x16_bf16 v[148:163], v[168:171], v[100:103], v[148:163]
	ds_read_b64_tr_b16 v[230:231], v211 offset:13376
	ds_read_b64_tr_b16 v[232:233], v211 offset:14912
	v_add_f32_e32 v15, v15, v213
	v_add_f32_e32 v248, v248, v249
	v_exp_f32_e32 v80, v80
	v_exp_f32_e32 v81, v81
	s_waitcnt lgkmcnt(7)
	v_mfma_f32_32x32x16_bf16 v[148:163], v[172:175], v[104:107], v[148:163]
	ds_read_b64_tr_b16 v[234:235], v211 offset:16384
	ds_read_b64_tr_b16 v[236:237], v211 offset:17920
	v_exp_f32_e32 v82, v82
	v_exp_f32_e32 v83, v83
	v_add_f32_e32 v14, v14, v15
	v_add_f32_e32 v14, v14, v248
	s_waitcnt lgkmcnt(8)
	v_mfma_f32_32x32x16_bf16 v[148:163], v[214:217], v[108:111], v[148:163]
	ds_read_b64_tr_b16 v[238:239], v211 offset:16448
	ds_read_b64_tr_b16 v[240:241], v211 offset:17984
	v_add_f32_e32 v15, v80, v81
	v_add_f32_e32 v213, v82, v83
	v_exp_f32_e32 v84, v84
	v_exp_f32_e32 v85, v85
	s_waitcnt lgkmcnt(9)
	v_mfma_f32_32x32x16_bf16 v[148:163], v[218:221], v[112:115], v[148:163]
	v_exp_f32_e32 v86, v86
	v_exp_f32_e32 v87, v87
	v_add_f32_e32 v15, v15, v213
	v_add_f32_e32 v213, v84, v85
	s_waitcnt lgkmcnt(8)
	v_mfma_f32_32x32x16_bf16 v[148:163], v[222:225], v[116:119], v[148:163]
	v_add_f32_e32 v248, v86, v87
	v_cvt_pk_bf16_f32 v80, v80, v81
	v_cvt_pk_bf16_f32 v81, v82, v83
	v_cvt_pk_bf16_f32 v82, v84, v85
	v_cvt_pk_bf16_f32 v83, v86, v87
	s_waitcnt lgkmcnt(6)
	v_mfma_f32_32x32x16_bf16 v[32:47], v[226:229], v[64:67], v[32:47]
	ds_read_b64_tr_b16 v[226:227], v211 offset:19456
	ds_read_b64_tr_b16 v[228:229], v211 offset:20992
	v_exp_f32_e32 v88, v88
	v_exp_f32_e32 v89, v89
	v_exp_f32_e32 v90, v90
	v_exp_f32_e32 v91, v91
	s_waitcnt lgkmcnt(6)
	v_mfma_f32_32x32x16_bf16 v[16:31], v[230:233], v[64:67], v[16:31]
	ds_read_b64_tr_b16 v[230:231], v211 offset:19520
	ds_read_b64_tr_b16 v[232:233], v211 offset:21056
	v_add_f32_e32 v213, v213, v248
	v_add_f32_e32 v15, v15, v213
	v_exp_f32_e32 v92, v92
	v_exp_f32_e32 v93, v93
	s_waitcnt lgkmcnt(6)
	v_mfma_f32_32x32x16_bf16 v[32:47], v[234:237], v[68:71], v[32:47]
	ds_read_b64_tr_b16 v[234:235], v211 offset:22528
	ds_read_b64_tr_b16 v[236:237], v211 offset:24064
	v_exp_f32_e32 v94, v94
	v_exp_f32_e32 v95, v95
	v_add_f32_e32 v213, v88, v89
	v_add_f32_e32 v248, v90, v91
	s_waitcnt lgkmcnt(6)
	v_mfma_f32_32x32x16_bf16 v[16:31], v[238:241], v[68:71], v[16:31]
	ds_read_b64_tr_b16 v[238:239], v211 offset:22592
	ds_read_b64_tr_b16 v[240:241], v211 offset:24128
	s_cmp_lg_u32 s56, 0
	s_cbranch_scc1 .Lmla_mask0

.Lmla_nostag1:
	s_add_i32 s66, s65, 1
	s_add_i32 s42, s66, 3
	s_min_u32 s42, s42, s44
	s_lshl_b64 s[6:7], s[42:43], 17
	v_lshl_add_u64 v[242:243], v[190:191], 0, s[6:7]
	s_lshl_b64 s[6:7], s[42:43], 12
	v_lshl_add_u64 v[244:245], v[194:195], 0, s[6:7]
	s_add_i32 s42, s66, 2
	s_min_u32 s42, s42, s44
	s_lshl_b64 s[6:7], s[42:43], 17
	v_lshl_add_u64 v[246:247], v[192:193], 0, s[6:7]
	global_load_dwordx4 v[120:123], v[242:243], off
	global_load_dwordx4 v[124:127], v[246:247], off
	global_load_dwordx4 v[128:131], v[244:245], off
	s_cmp_ge_u32 s66, s45
	s_cbranch_scc1 .Lmla_skip1
	s_add_i32 s41, s66, 1
	s_cmp_ge_u32 s41, s64
	s_cselect_b32 s7, 1, 0
	s_cmp_lt_u32 s41, s45
	s_cselect_b32 s26, 1, 0
	s_and_b32 s56, s7, s26
	s_lshl_b32 s27, s41, 6
	ds_read_b128 v[164:167], v210 offset:0
	ds_read_b128 v[168:171], v210 offset:32
	ds_read_b128 v[172:175], v210 offset:64
	ds_read_b128 v[214:217], v210 offset:96
	ds_read_b128 v[218:221], v210 offset:128
	ds_read_b128 v[222:225], v210 offset:160
	v_exp_f32_e32 v132, v132
	v_exp_f32_e32 v133, v133
	v_exp_f32_e32 v134, v134
	v_exp_f32_e32 v135, v135
	s_waitcnt lgkmcnt(5)
	v_mfma_f32_32x32x16_bf16 v[64:79], v[164:167], v[96:99], v[48:63]
	ds_read_b128 v[164:167], v210 offset:6656
	v_add_f32_e32 v14, v132, v133
	v_add_f32_e32 v15, v134, v135
	v_exp_f32_e32 v136, v136
	v_exp_f32_e32 v137, v137
	s_waitcnt lgkmcnt(5)
	v_mfma_f32_32x32x16_bf16 v[64:79], v[168:171], v[100:103], v[64:79]
	ds_read_b128 v[168:171], v210 offset:6688
	v_exp_f32_e32 v138, v138
	v_exp_f32_e32 v139, v139
	v_add_f32_e32 v14, v14, v15
	v_add_f32_e32 v15, v136, v137
	s_waitcnt lgkmcnt(5)
	v_mfma_f32_32x32x16_bf16 v[64:79], v[172:175], v[104:107], v[64:79]
	ds_read_b128 v[172:175], v210 offset:6720
	v_add_f32_e32 v213, v138, v139
	v_cvt_pk_bf16_f32 v132, v132, v133
	v_cvt_pk_bf16_f32 v133, v134, v135
	v_cvt_pk_bf16_f32 v134, v136, v137
	v_cvt_pk_bf16_f32 v135, v138, v139
	s_waitcnt lgkmcnt(5)
	v_mfma_f32_32x32x16_bf16 v[64:79], v[214:217], v[108:111], v[64:79]
	ds_read_b128 v[214:217], v210 offset:6752
	v_exp_f32_e32 v140, v140
	v_exp_f32_e32 v141, v141
	v_exp_f32_e32 v142, v142
	v_exp_f32_e32 v143, v143
	s_waitcnt lgkmcnt(5)
	v_mfma_f32_32x32x16_bf16 v[64:79], v[218:221], v[112:115], v[64:79]
	ds_read_b128 v[218:221], v210 offset:6784
	v_add_f32_e32 v14, v14, v15
	v_add_f32_e32 v14, v14, v213
	v_exp_f32_e32 v144, v144
	v_exp_f32_e32 v145, v145
	s_waitcnt lgkmcnt(5)
	v_mfma_f32_32x32x16_bf16 v[64:79], v[222:225], v[116:119], v[64:79]
	ds_read_b128 v[222:225], v210 offset:6816
	v_exp_f32_e32 v146, v146
	v_exp_f32_e32 v147, v147
	v_add_f32_e32 v15, v140, v141
	v_add_f32_e32 v213, v142, v143
	s_waitcnt lgkmcnt(5)
	v_mfma_f32_32x32x16_bf16 v[80:95], v[164:167], v[96:99], v[48:63]
	ds_read_b64_tr_b16 v[226:227], v211 offset:38912
	ds_read_b64_tr_b16 v[228:229], v211 offset:40448
	v_add_f32_e32 v248, v144, v145
	v_add_f32_e32 v249, v146, v147
	v_cvt_pk_bf16_f32 v136, v140, v141
	v_cvt_pk_bf16_f32 v137, v142, v143
	v_cvt_pk_bf16_f32 v138, v144, v145
	v_cvt_pk_bf16_f32 v139, v146, v147
	s_waitcnt lgkmcnt(6)
	v_mfma_f32_32x32x16_bf16 v[80:95], v[168:171], v[100:103], v[80:95]
	ds_read_b64_tr_b16 v[230:231], v211 offset:38976
	ds_read_b64_tr_b16 v[232:233], v211 offset:40512
	v_add_f32_e32 v15, v15, v213
	v_add_f32_e32 v248, v248, v249
	v_exp_f32_e32 v148, v148
	v_exp_f32_e32 v149, v149
	s_waitcnt lgkmcnt(7)
	v_mfma_f32_32x32x16_bf16 v[80:95], v[172:175], v[104:107], v[80:95]
	ds_read_b64_tr_b16 v[234:235], v211 offset:41984
	ds_read_b64_tr_b16 v[236:237], v211 offset:43520
	v_exp_f32_e32 v150, v150
	v_exp_f32_e32 v151, v151
	v_add_f32_e32 v14, v14, v15
	v_add_f32_e32 v14, v14, v248
	s_waitcnt lgkmcnt(8)
	v_mfma_f32_32x32x16_bf16 v[80:95], v[214:217], v[108:111], v[80:95]
	ds_read_b64_tr_b16 v[238:239], v211 offset:42048
	ds_read_b64_tr_b16 v[240:241], v211 offset:43584
	v_add_f32_e32 v15, v148, v149
	v_add_f32_e32 v213, v150, v151
	v_exp_f32_e32 v152, v152
	v_exp_f32_e32 v153, v153
	s_waitcnt lgkmcnt(9)
	v_mfma_f32_32x32x16_bf16 v[80:95], v[218:221], v[112:115], v[80:95]
	v_exp_f32_e32 v154, v154
	v_exp_f32_e32 v155, v155
	v_add_f32_e32 v15, v15, v213
	v_add_f32_e32 v213, v152, v153
	s_waitcnt lgkmcnt(8)
	v_mfma_f32_32x32x16_bf16 v[80:95], v[222:225], v[116:119], v[80:95]
	v_add_f32_e32 v248, v154, v155
	v_cvt_pk_bf16_f32 v148, v148, v149
	v_cvt_pk_bf16_f32 v149, v150, v151
	v_cvt_pk_bf16_f32 v150, v152, v153
	v_cvt_pk_bf16_f32 v151, v154, v155
	s_waitcnt lgkmcnt(6)
	v_mfma_f32_32x32x16_bf16 v[32:47], v[226:229], v[132:135], v[32:47]
	ds_read_b64_tr_b16 v[226:227], v211 offset:45056
	ds_read_b64_tr_b16 v[228:229], v211 offset:46592
	v_exp_f32_e32 v156, v156
	v_exp_f32_e32 v157, v157
	v_exp_f32_e32 v158, v158
	v_exp_f32_e32 v159, v159
	s_waitcnt lgkmcnt(6)
	v_mfma_f32_32x32x16_bf16 v[16:31], v[230:233], v[132:135], v[16:31]
	ds_read_b64_tr_b16 v[230:231], v211 offset:45120
	ds_read_b64_tr_b16 v[232:233], v211 offset:46656
	v_add_f32_e32 v213, v213, v248
	v_add_f32_e32 v15, v15, v213
	v_exp_f32_e32 v160, v160
	v_exp_f32_e32 v161, v161
	s_waitcnt lgkmcnt(6)
	v_mfma_f32_32x32x16_bf16 v[32:47], v[234:237], v[136:139], v[32:47]
	ds_read_b64_tr_b16 v[234:235], v211 offset:48128
	ds_read_b64_tr_b16 v[236:237], v211 offset:49664
	v_exp_f32_e32 v162, v162
	v_exp_f32_e32 v163, v163
	v_add_f32_e32 v213, v156, v157
	v_add_f32_e32 v248, v158, v159
	s_waitcnt lgkmcnt(6)
	v_mfma_f32_32x32x16_bf16 v[16:31], v[238:241], v[136:139], v[16:31]
	ds_read_b64_tr_b16 v[238:239], v211 offset:48192
	ds_read_b64_tr_b16 v[240:241], v211 offset:49728
	s_cmp_lg_u32 s56, 0
	s_cbranch_scc1 .Lmla_mask1
